# mix_b2: selection row of the next item loaded one item ahead into three registers freed by renaming (lane-id copies), on top of the prep_c prefetch version
# baseline (speedup 1.0000x reference)
; DI void phase_mix_b2(int wv_, int vb_, int nvb_, char* ws_, const Ctx& p, char* smem) {
;     ...
;   {
;     const int tid = tidx(wv_);
;     for (int i = tid; i < 512; i += 256) sbias[i] = p.rel_bias[(i >> 4) * 40 + 24 + (i & 15)] * 1.4426950408889634f;
;     if (tid < 16) sbias[512 + tid] = -INFINITY;
;   }
;   __syncthreads();
;   for (int ib = vb_; ib < 32768; ib += nvb_) {
;     const int tid = tidx(wv_); const int lane = tid & 63, wave = tid >> 6, n16 = tid & 15, fq = (tid >> 4) & 3;
;     const int b = ib & 7, r4 = ib >> 3, hkv = r4 >> 10, t = (r4 & 1023) * 4 + wave;
;     const u16* Pb = P + (size_t)b * SEQ * 2304;
;     u16* mySel = selL + wave * 256;
;     unsigned char* mySelb = selbL + wave * 256;
;     const size_t qrow = (size_t)b * SEQ + t;
;     asm volatile("s_waitcnt lgkmcnt(0)" ::: "memory");
;     *(uint2*)(mySel + lane * 4) = *(const uint2*)((const u16*)(ws_ + WS_SEL) + qrow * 256 + lane * 4);
;     *(unsigned*)(mySelb + lane * 4) = *(const unsigned*)((const unsigned char*)(ws_ + WS_SELB) + qrow * 256 + lane * 4);
;     asm volatile("s_waitcnt lgkmcnt(0)" ::: "memory");
.LBB0_348:
	s_or_b64 exec, exec, s[2:3]
	v_cmp_gt_i32_e32 vcc, 16, v2
	s_and_saveexec_b64 s[2:3], vcc
	v_lshl_add_u32 v0, v2, 2, v216
	ds_write_b32 v0, v207 offset:2048
	s_or_b64 exec, exec, s[2:3]
	v_readlane_b32 s0, v252, 20
	v_readlane_b32 s1, v252, 21
	s_andn2_b64 vcc, exec, s[0:1]
	s_waitcnt lgkmcnt(0)
	s_barrier
	s_cbranch_vccnz .LBB0_357
	s_add_u32 s2, s78, 0x13c00000
	s_addc_u32 s3, s79, 0
	s_add_u32 s4, s78, 0x15000000
	v_readlane_b32 s0, v254, 14
	v_add_u32_e32 v217, 0x10840, v214
	v_add_u32_e32 v218, 0x11040, v214
	s_addc_u32 s5, s79, 0
	v_readlane_b32 s10, v253, 50
	s_mov_b32 s11, s0
	v_readlane_b32 s1, v254, 15
	v_lshl_or_b32 v6, s33, 6, v204
	v_ashrrev_i32_e32 v6, 6, v6
	s_and_b32 s9, s10, 0x7000
	s_lshr_b32 s8, s11, 1
	s_and_b32 s8, s8, 0xffc
	s_add_i32 s8, s8, s9
	v_add_u32_e32 v6, s8, v6
	v_lshlrev_b32_e32 v7, 8, v6
	v_lshlrev_b32_e32 v6, 9, v6
	v_lshl_add_u32 v6, v204, 3, v6
	v_lshl_add_u32 v7, v204, 2, v7
	global_load_dwordx2 v[220:221], v6, s[2:3]
	global_load_dword v222, v7, s[4:5]
	s_waitcnt vmcnt(0)
	s_branch .LBB0_353

; #define LOADKV(BASECOL, SH) { _Pragma("unroll") for (int rr = 0; rr < 16; ++rr) { \
;       const unsigned vo_ = (unsigned)mySel[(SH) * 128 + rr * 8 + (lane >> 3)] * 4608u + (unsigned)(hkv * 128 + (lane & 7) * 16); \
;       vreg[rr] = *(const bf16x8*)((const char*)(Pb + (BASECOL)) + (size_t)vo_); } }
; DI void phase_mix_b2(int wv_, int vb_, int nvb_, char* ws_, const Ctx& p, char* smem) {
;     ...
;   for (int ib = vb_; ib < 32768; ib += nvb_) {
;     const int tid = tidx(wv_); const int lane = tid & 63, wave = tid >> 6, n16 = tid & 15, fq = (tid >> 4) & 3;
;     const int b = ib & 7, r4 = ib >> 3, hkv = r4 >> 10, t = (r4 & 1023) * 4 + wave;
;     const u16* Pb = P + (size_t)b * SEQ * 2304;
;     u16* mySel = selL + wave * 256;
;     unsigned char* mySelb = selbL + wave * 256;
;     const size_t qrow = (size_t)b * SEQ + t;
;     asm volatile("s_waitcnt lgkmcnt(0)" ::: "memory");
;     *(uint2*)(mySel + lane * 4) = *(const uint2*)((const u16*)(ws_ + WS_SEL) + qrow * 256 + lane * 4);
;     *(unsigned*)(mySelb + lane * 4) = *(const unsigned*)((const unsigned char*)(ws_ + WS_SELB) + qrow * 256 + lane * 4);
;     asm volatile("s_waitcnt lgkmcnt(0)" ::: "memory");
;     bf16x8 qf[2];
;     {
;       const u16* qp = Pb + (size_t)t * 2304 + (hkv * 4 + (n16 & 3)) * 64 + fq * 8;
;       qf[0] = *(const bf16x8*)qp; qf[1] = *(const bf16x8*)(qp + 32);
;       if (n16 >= 4) { qf[0] = zero8(); qf[1] = zero8(); }
;     }
;     f32x4 lg[16];
;     char* Ks = smem + wave * 16384;
;     bf16x8 vreg[16];
;     ...
;     bf16x8 vreg2[16];
;     ...
;     LOADKV(1024, 0)
.LBB0_353:
	s_mov_b32 s0, s33
	s_nop 0
	s_and_b32 s84, s10, 0x7000
	v_lshl_or_b32 v10, s0, 6, v204
	s_lshr_b32 s0, s11, 1
	v_ashrrev_i32_e32 v126, 6, v10
	s_and_b32 s0, s0, 0xffc
	v_add_u32_e32 v2, s0, v126
	v_ashrrev_i32_e32 v3, 31, v2
	v_lshl_add_u64 v[200:201], v[2:3], 0, s[84:85]
	s_nop 0
	v_lshlrev_b64 v[6:7], 9, v[200:201]
	v_lshlrev_b64 v[4:5], 8, v[200:201]
	v_lshl_add_u64 v[6:7], s[2:3], 0, v[6:7]
	v_lshlrev_b32_e32 v8, 3, v204
	v_mov_b32_e32 v9, v1
	s_waitcnt lgkmcnt(0)
	v_lshlrev_b32_e32 v0, 2, v204
	v_lshl_add_u64 v[6:7], v[6:7], 0, v[8:9]
	v_lshl_add_u64 v[4:5], s[4:5], 0, v[4:5]
	v_lshl_add_u64 v[4:5], v[4:5], 0, v[0:1]
	s_nop 0
	s_nop 0
	s_nop 0
	s_ashr_i32 s12, s11, 13
	s_mul_i32 s0, s84, 0x1200
	s_add_u32 s6, s86, s0
	v_and_b32_e32 v14, 3, v204
	s_addc_u32 s7, s87, 0
	v_lshl_or_b32 v227, s12, 2, v14
	v_lshl_add_u32 v11, v126, 9, v217
	v_mov_b64_e32 v[4:5], s[6:7]
	v_lshlrev_b32_e32 v12, 6, v227
	v_bfe_u32 v219, v10, 4, 2
	v_lshl_add_u32 v202, v126, 8, v218
	v_add_u32_e32 v15, v11, v8
	v_mad_i64_i32 v[2:3], s[0:1], v2, s50, v[4:5]
	v_ashrrev_i32_e32 v13, 31, v12
	v_add_u32_e32 v16, v202, v0
	v_lshl_add_u64 v[2:3], v[12:13], 1, v[2:3]
	v_lshlrev_b32_e32 v0, 4, v219
	v_lshl_add_u64 v[8:9], v[2:3], 0, v[0:1]
	v_and_b32_e32 v0, 15, v204
	v_cmp_lt_u32_e32 vcc, 3, v0
	s_waitcnt vmcnt(16)
	ds_write_b64 v15, v[220:221]
	ds_write_b32 v16, v222
	v_readlane_b32 s8, v254, 56
	v_readlane_b32 s9, v253, 56
	s_add_i32 s8, s11, s8
	s_add_i32 s9, s10, s9
	s_and_b32 s9, s9, 0x7000
	s_lshr_b32 s8, s8, 1
	s_and_b32 s8, s8, 0xffc
	s_add_i32 s8, s8, s9
	v_add_u32_e32 v6, s8, v126
	v_lshlrev_b32_e32 v7, 8, v6
	v_lshlrev_b32_e32 v6, 9, v6
	v_lshl_add_u32 v6, v204, 3, v6
	v_lshl_add_u32 v7, v204, 2, v7
	global_load_dwordx2 v[220:221], v6, s[2:3]
	global_load_dword v222, v7, s[4:5]
	s_waitcnt lgkmcnt(0)
	global_load_dwordx4 v[2:5], v[8:9], off
	s_nop 0
	global_load_dwordx4 v[6:9], v[8:9], off offset:64
	s_and_saveexec_b64 s[8:9], vcc
	s_cbranch_execz .LBB0_355
	s_waitcnt vmcnt(1)
	v_mov_b32_e32 v2, v1
	v_mov_b32_e32 v3, v1
	v_perm_b32 v2, v2, v2, s48
	s_waitcnt vmcnt(0)
	v_perm_b32 v6, v3, v3, s48
	v_mov_b32_e32 v3, v2
	v_mov_b32_e32 v4, v2
	v_mov_b32_e32 v5, v2
	v_mov_b32_e32 v7, v6
	v_mov_b32_e32 v8, v6
	v_mov_b32_e32 v9, v6
.LBB0_355:
	s_or_b64 exec, exec, s[8:9]
	v_lshrrev_b32_e32 v127, 3, v204
	v_lshlrev_b32_e32 v224, 4, v204
	v_lshrrev_b32_e32 v223, 4, v10
	v_and_b32_e32 v10, 0x70, v224
	v_lshl_add_u32 v226, v127, 1, v11
	v_lshl_or_b32 v203, s12, 7, v10
	ds_read_u16 v10, v226
	ds_read_u16 v14, v226 offset:16
	ds_read_u16 v18, v226 offset:32
	ds_read_u16 v22, v226 offset:48
	ds_read_u16 v26, v226 offset:64
	ds_read_u16 v30, v226 offset:80
	ds_read_u16 v34, v226 offset:96
	ds_read_u16 v38, v226 offset:112
	ds_read_u16 v42, v226 offset:128
	ds_read_u16 v50, v226 offset:272
	ds_read_u16 v114, v226 offset:416
	ds_read_u16 v58, v226 offset:288
	ds_read_u16 v118, v226 offset:432
	s_waitcnt lgkmcnt(4)
	v_mad_u32_u24 v42, v42, s50, v203
	s_waitcnt lgkmcnt(3)
	v_mad_u32_u24 v50, v50, s50, v203
	global_load_dwordx4 v[46:49], v42, s[6:7] offset:2048
	s_waitcnt lgkmcnt(1)
	v_mad_u32_u24 v58, v58, s50, v203
	global_load_dwordx4 v[50:53], v50, s[6:7] offset:2048
	ds_read_u16 v42, v226 offset:144
	global_load_dwordx4 v[58:61], v58, s[6:7] offset:2048
	ds_read_u16 v66, v226 offset:304
	ds_read_u16 v122, v226 offset:448
	ds_read_u16 v74, v226 offset:320
	ds_read_u16 v128, v226 offset:464
	s_waitcnt lgkmcnt(4)
	v_mad_u32_u24 v42, v42, s50, v203
	global_load_dwordx4 v[54:57], v42, s[6:7] offset:2048
	ds_read_u16 v42, v226 offset:160
	s_waitcnt lgkmcnt(4)
	v_mad_u32_u24 v66, v66, s50, v203
	global_load_dwordx4 v[66:69], v66, s[6:7] offset:2048
	s_waitcnt lgkmcnt(2)
	v_mad_u32_u24 v74, v74, s50, v203
	global_load_dwordx4 v[74:77], v74, s[6:7] offset:2048
	s_waitcnt lgkmcnt(0)
	v_mad_u32_u24 v42, v42, s50, v203
	global_load_dwordx4 v[62:65], v42, s[6:7] offset:2048
	ds_read_u16 v42, v226 offset:176
	ds_read_u16 v82, v226 offset:336
	ds_read_u16 v132, v226 offset:480
	ds_read_u16 v90, v226 offset:352
	ds_read_u16 v136, v226 offset:496
	s_waitcnt lgkmcnt(4)
	v_mad_u32_u24 v42, v42, s50, v203
	global_load_dwordx4 v[70:73], v42, s[6:7] offset:2048
	ds_read_u16 v42, v226 offset:192
	s_waitcnt lgkmcnt(4)
	v_mad_u32_u24 v82, v82, s50, v203
	global_load_dwordx4 v[82:85], v82, s[6:7] offset:2048
	v_mad_u32_u24 v10, v10, s50, v203
	global_load_dwordx4 v[10:13], v10, s[6:7] offset:2048
	s_waitcnt lgkmcnt(0)
	v_mad_u32_u24 v42, v42, s50, v203
	global_load_dwordx4 v[78:81], v42, s[6:7] offset:2048
	ds_read_u16 v42, v226 offset:208
	v_mad_u32_u24 v14, v14, s50, v203
	global_load_dwordx4 v[14:17], v14, s[6:7] offset:2048
	v_mad_u32_u24 v18, v18, s50, v203
	global_load_dwordx4 v[18:21], v18, s[6:7] offset:2048
	v_mad_u32_u24 v22, v22, s50, v203
	s_waitcnt lgkmcnt(0)
	v_mad_u32_u24 v42, v42, s50, v203
	v_mad_u32_u24 v90, v90, s50, v203
	global_load_dwordx4 v[22:25], v22, s[6:7] offset:2048
	v_mad_u32_u24 v26, v26, s50, v203
	global_load_dwordx4 v[86:89], v42, s[6:7] offset:2048
	ds_read_u16 v98, v226 offset:368
	global_load_dwordx4 v[90:93], v90, s[6:7] offset:2048
	ds_read_u16 v42, v226 offset:224
	global_load_dwordx4 v[26:29], v26, s[6:7] offset:2048
	v_mad_u32_u24 v30, v30, s50, v203
	global_load_dwordx4 v[30:33], v30, s[6:7] offset:2048
	v_mad_u32_u24 v34, v34, s50, v203
	global_load_dwordx4 v[34:37], v34, s[6:7] offset:2048
	v_mad_u32_u24 v38, v38, s50, v203
	global_load_dwordx4 v[38:41], v38, s[6:7] offset:2048
	s_waitcnt lgkmcnt(0)
; #define LOADKV(BASECOL, SH) { _Pragma("unroll") for (int rr = 0; rr < 16; ++rr) { \
;       const unsigned vo_ = (unsigned)mySel[(SH) * 128 + rr * 8 + (lane >> 3)] * 4608u + (unsigned)(hkv * 128 + (lane & 7) * 16); \
;       vreg[rr] = *(const bf16x8*)((const char*)(Pb + (BASECOL)) + (size_t)vo_); } }
; #define LOADV(SH) LOADKV(1280, SH)
; #define KWRITE() { _Pragma("unroll") for (int rr = 0; rr < 16; ++rr) { const int row_ = rr * 8 + (lane >> 3), piece_ = lane & 7; \
;       *(bf16x8*)(Ks + row_ * 128 + ((piece_ ^ (row_ & 7)) * 16)) = vreg[rr]; } }
; #define LOADKV2(BASECOL, SH) { _Pragma("unroll") for (int rr = 0; rr < 16; ++rr) { \
;       const unsigned vo_ = (unsigned)mySel[(SH) * 128 + rr * 8 + (lane >> 3)] * 4608u + (unsigned)(hkv * 128 + (lane & 7) * 16); \
;       vreg2[rr] = *(const bf16x8*)((const char*)(Pb + (BASECOL)) + (size_t)vo_); } }
; #define KWRITE2() { _Pragma("unroll") for (int rr = 0; rr < 16; ++rr) { const int row_ = rr * 8 + (lane >> 3), piece_ = lane & 7; \
;       *(bf16x8*)(Ks + row_ * 128 + ((piece_ ^ (row_ & 7)) * 16)) = vreg2[rr]; } }
; DI void phase_mix_b2(int wv_, int vb_, int nvb_, char* ws_, const Ctx& p, char* smem) {
;     ...
;     bf16x8 vreg2[16];
;     ...
;     LOADKV(1024, 0)
;     LOADKV2(1024, 1)
;     asm volatile("s_waitcnt lgkmcnt(0)" ::: "memory");
;     KWRITE()
;     asm volatile("s_waitcnt lgkmcnt(0)" ::: "memory");
;     QKSTAGE(0)
;     asm volatile("s_waitcnt lgkmcnt(0)" ::: "memory");
;     KWRITE2()
;     LOADV(0)
;     asm volatile("s_waitcnt lgkmcnt(0)" ::: "memory");
;     QKSTAGE(1)
	v_mad_u32_u24 v42, v42, s50, v203
	v_mad_u32_u24 v98, v98, s50, v203
	global_load_dwordx4 v[94:97], v42, s[6:7] offset:2048
	ds_read_u16 v102, v226 offset:384
	global_load_dwordx4 v[98:101], v98, s[6:7] offset:2048
	ds_read_u16 v42, v226 offset:240
	ds_read_u16 v110, v226 offset:400
	v_lshlrev_b32_e32 v140, 7, v127
	s_waitcnt lgkmcnt(2)
	v_mad_u32_u24 v102, v102, s50, v203
	global_load_dwordx4 v[102:105], v102, s[6:7] offset:2048
	s_waitcnt lgkmcnt(1)
	v_mad_u32_u24 v42, v42, s50, v203
	global_load_dwordx4 v[106:109], v42, s[6:7] offset:2048
	ds_read_u16 v42, v226 offset:256
	v_bitop3_b32 v127, v127, v204, 7 bitop3:0x78
	s_waitcnt lgkmcnt(1)
	v_mad_u32_u24 v110, v110, s50, v203
	v_lshl_add_u32 v225, v126, 14, v214
	v_lshlrev_b32_e32 v127, 4, v127
	s_waitcnt lgkmcnt(0)
	v_mad_u32_u24 v42, v42, s50, v203
	global_load_dwordx4 v[42:45], v42, s[6:7] offset:2048
	v_mad_u32_u24 v114, v114, s50, v203
	global_load_dwordx4 v[110:113], v110, s[6:7] offset:2048
	v_mad_u32_u24 v118, v118, s50, v203
	v_mad_u32_u24 v122, v122, s50, v203
	v_mad_u32_u24 v128, v128, s50, v203
	v_mad_u32_u24 v132, v132, s50, v203
	v_mad_u32_u24 v136, v136, s50, v203
	v_add3_u32 v127, v225, v127, v140
	global_load_dwordx4 v[114:117], v114, s[6:7] offset:2048
	v_and_b32_e32 v126, 7, v204
	global_load_dwordx4 v[118:121], v118, s[6:7] offset:2048
	v_lshlrev_b32_e32 v228, 2, v227
	global_load_dwordx4 v[122:125], v122, s[6:7] offset:2048
	v_cmp_eq_u32_e32 vcc, 0, v219
	global_load_dwordx4 v[128:131], v128, s[6:7] offset:2048
	s_nop 0
	global_load_dwordx4 v[132:135], v132, s[6:7] offset:2048
	s_nop 0
	global_load_dwordx4 v[136:139], v136, s[6:7] offset:2048
	s_waitcnt lgkmcnt(0)
	s_waitcnt vmcnt(22)
	ds_write_b128 v127, v[10:13]
	s_waitcnt vmcnt(20)
	ds_write_b128 v127, v[14:17] offset:1024
	s_waitcnt vmcnt(19)
	ds_write_b128 v127, v[18:21] offset:2048
	s_waitcnt vmcnt(18)
	ds_write_b128 v127, v[22:25] offset:3072
	s_waitcnt vmcnt(15)
	ds_write_b128 v127, v[26:29] offset:4096
	s_waitcnt vmcnt(14)
	ds_write_b128 v127, v[30:33] offset:5120
	s_waitcnt vmcnt(13)
	ds_write_b128 v127, v[34:37] offset:6144
	s_waitcnt vmcnt(12)
	ds_write_b128 v127, v[38:41] offset:7168
	ds_write_b128 v127, v[46:49] offset:8192
	ds_write_b128 v127, v[54:57] offset:9216
	ds_write_b128 v127, v[62:65] offset:10240
	ds_write_b128 v127, v[70:73] offset:11264
	ds_write_b128 v127, v[78:81] offset:12288
	ds_write_b128 v127, v[86:89] offset:13312
	s_waitcnt vmcnt(11)
	ds_write_b128 v127, v[94:97] offset:14336
	s_waitcnt vmcnt(8)
	ds_write_b128 v127, v[106:109] offset:15360
	v_bitop3_b32 v10, v219, v204, 7 bitop3:0x78
	v_lshl_add_u32 v16, v0, 7, v225
	s_waitcnt lgkmcnt(0)
	v_lshl_add_u32 v10, v10, 4, v16
	ds_read_b128 v[12:15], v10
	v_bitop3_b32 v11, v219, v126, 4 bitop3:0x36
	v_lshl_add_u32 v11, v11, 4, v16
	ds_read_b128 v[16:19], v11
	s_waitcnt lgkmcnt(1)
	v_mfma_f32_16x16x32_bf16 v[12:15], v[12:15], v[2:5], 0
	s_waitcnt lgkmcnt(0)
	v_mfma_f32_16x16x32_bf16 v[190:193], v[16:19], v[6:9], v[12:15]
	s_nop 5
	ds_read_b128 v[12:15], v10 offset:2048
	ds_read_b128 v[16:19], v11 offset:2048
	s_waitcnt lgkmcnt(1)
	v_mfma_f32_16x16x32_bf16 v[12:15], v[12:15], v[2:5], 0
	s_waitcnt lgkmcnt(0)
	v_mfma_f32_16x16x32_bf16 v[186:189], v[16:19], v[6:9], v[12:15]
	s_nop 5
	ds_read_b128 v[12:15], v10 offset:4096
	ds_read_b128 v[16:19], v11 offset:4096
	s_waitcnt lgkmcnt(1)
	v_mfma_f32_16x16x32_bf16 v[12:15], v[12:15], v[2:5], 0
	s_waitcnt lgkmcnt(0)
	v_mfma_f32_16x16x32_bf16 v[182:185], v[16:19], v[6:9], v[12:15]
	s_nop 5
	ds_read_b128 v[12:15], v10 offset:6144
	ds_read_b128 v[16:19], v11 offset:6144
	s_waitcnt lgkmcnt(1)
	v_mfma_f32_16x16x32_bf16 v[12:15], v[12:15], v[2:5], 0
	s_waitcnt lgkmcnt(0)
	v_mfma_f32_16x16x32_bf16 v[178:181], v[16:19], v[6:9], v[12:15]
	s_nop 5
	ds_read_b128 v[12:15], v10 offset:8192
	ds_read_b128 v[16:19], v11 offset:8192
	s_waitcnt lgkmcnt(1)
	v_mfma_f32_16x16x32_bf16 v[12:15], v[12:15], v[2:5], 0
	s_waitcnt lgkmcnt(0)
	v_mfma_f32_16x16x32_bf16 v[174:177], v[16:19], v[6:9], v[12:15]
	s_nop 5
	ds_read_b128 v[12:15], v10 offset:10240
	ds_read_b128 v[16:19], v11 offset:10240
	s_waitcnt lgkmcnt(1)
	v_mfma_f32_16x16x32_bf16 v[12:15], v[12:15], v[2:5], 0
	s_waitcnt lgkmcnt(0)
	v_mfma_f32_16x16x32_bf16 v[166:169], v[16:19], v[6:9], v[12:15]
	s_nop 5
	ds_read_b128 v[12:15], v10 offset:12288
	ds_read_b128 v[16:19], v11 offset:12288
	s_waitcnt lgkmcnt(1)
	v_mfma_f32_16x16x32_bf16 v[12:15], v[12:15], v[2:5], 0
	s_waitcnt lgkmcnt(0)
	v_mfma_f32_16x16x32_bf16 v[158:161], v[16:19], v[6:9], v[12:15]
	s_nop 5
	ds_read_b128 v[12:15], v10 offset:14336
	ds_read_b128 v[16:19], v11 offset:14336
	s_waitcnt lgkmcnt(0)
	s_waitcnt vmcnt(7)
	ds_write_b128 v127, v[42:45]
	ds_write_b128 v127, v[50:53] offset:1024
	ds_write_b128 v127, v[58:61] offset:2048
	ds_write_b128 v127, v[66:69] offset:3072
	ds_write_b128 v127, v[74:77] offset:4096
	ds_write_b128 v127, v[82:85] offset:5120
	ds_write_b128 v127, v[90:93] offset:6144
	ds_write_b128 v127, v[98:101] offset:7168
	ds_write_b128 v127, v[102:105] offset:8192
	s_waitcnt vmcnt(6)
	ds_write_b128 v127, v[110:113] offset:9216
	s_waitcnt vmcnt(5)
	ds_write_b128 v127, v[114:117] offset:10240
	s_waitcnt vmcnt(4)
	ds_write_b128 v127, v[118:121] offset:11264
	s_waitcnt vmcnt(3)
	ds_write_b128 v127, v[122:125] offset:12288
	s_waitcnt vmcnt(2)
	ds_write_b128 v127, v[128:131] offset:13312
	s_waitcnt vmcnt(1)
	ds_write_b128 v127, v[132:135] offset:14336
	s_waitcnt vmcnt(0)
	ds_write_b128 v127, v[136:139] offset:15360
	s_waitcnt lgkmcnt(14)
	v_mfma_f32_16x16x32_bf16 v[12:15], v[12:15], v[2:5], 0
	v_mfma_f32_16x16x32_bf16 v[150:153], v[16:19], v[6:9], v[12:15]
	s_nop 6
	ds_read_u16 v12, v226
	ds_read_u16 v13, v226 offset:16
	ds_read_u16 v14, v226 offset:32
	ds_read_u16 v15, v226 offset:48
	s_waitcnt lgkmcnt(3)
; #define LOADV(SH) LOADKV(1280, SH)
; #define LOADKV2(BASECOL, SH) { _Pragma("unroll") for (int rr = 0; rr < 16; ++rr) { \
;       const unsigned vo_ = (unsigned)mySel[(SH) * 128 + rr * 8 + (lane >> 3)] * 4608u + (unsigned)(hkv * 128 + (lane & 7) * 16); \
;       vreg2[rr] = *(const bf16x8*)((const char*)(Pb + (BASECOL)) + (size_t)vo_); } }
; DI void phase_mix_b2(int wv_, int vb_, int nvb_, char* ws_, const Ctx& p, char* smem) {
;     ...
;     LOADV(0)
;     asm volatile("s_waitcnt lgkmcnt(0)" ::: "memory");
;     QKSTAGE(1)
;     asm volatile("s_waitcnt lgkmcnt(0)" ::: "memory");
;     LOADKV2(1280, 1)
	v_mad_u32_u24 v12, v12, s50, v203
	global_load_dwordx4 v[18:21], v12, s[6:7] offset:2560
	s_waitcnt lgkmcnt(2)
	v_mad_u32_u24 v12, v13, s50, v203
	global_load_dwordx4 v[22:25], v12, s[6:7] offset:2560
	s_waitcnt lgkmcnt(1)
	v_mad_u32_u24 v12, v14, s50, v203
	global_load_dwordx4 v[26:29], v12, s[6:7] offset:2560
	s_waitcnt lgkmcnt(0)
	v_mad_u32_u24 v12, v15, s50, v203
	global_load_dwordx4 v[30:33], v12, s[6:7] offset:2560
	ds_read_u16 v12, v226 offset:64
	s_waitcnt lgkmcnt(0)
	v_mad_u32_u24 v12, v12, s50, v203
	global_load_dwordx4 v[42:45], v12, s[6:7] offset:2560
	ds_read_u16 v12, v226 offset:80
	s_waitcnt lgkmcnt(0)
	v_mad_u32_u24 v12, v12, s50, v203
	global_load_dwordx4 v[50:53], v12, s[6:7] offset:2560
	ds_read_u16 v12, v226 offset:96
	s_waitcnt lgkmcnt(0)
	v_mad_u32_u24 v12, v12, s50, v203
	global_load_dwordx4 v[54:57], v12, s[6:7] offset:2560
	ds_read_u16 v12, v226 offset:112
	s_waitcnt lgkmcnt(0)
	v_mad_u32_u24 v12, v12, s50, v203
	global_load_dwordx4 v[62:65], v12, s[6:7] offset:2560
	ds_read_u16 v12, v226 offset:128
	s_waitcnt lgkmcnt(0)
	v_mad_u32_u24 v12, v12, s50, v203
	global_load_dwordx4 v[74:77], v12, s[6:7] offset:2560
	ds_read_u16 v12, v226 offset:144
	s_waitcnt lgkmcnt(0)
	v_mad_u32_u24 v12, v12, s50, v203
	global_load_dwordx4 v[82:85], v12, s[6:7] offset:2560
	ds_read_u16 v12, v226 offset:160
	s_waitcnt lgkmcnt(0)
	v_mad_u32_u24 v12, v12, s50, v203
	global_load_dwordx4 v[90:93], v12, s[6:7] offset:2560
	ds_read_u16 v12, v226 offset:176
	s_waitcnt lgkmcnt(0)
	v_mad_u32_u24 v12, v12, s50, v203
	global_load_dwordx4 v[98:101], v12, s[6:7] offset:2560
	ds_read_u16 v12, v226 offset:192
	s_waitcnt lgkmcnt(0)
	v_mad_u32_u24 v12, v12, s50, v203
	global_load_dwordx4 v[106:109], v12, s[6:7] offset:2560
	ds_read_u16 v12, v226 offset:208
	s_waitcnt lgkmcnt(0)
	v_mad_u32_u24 v12, v12, s50, v203
	global_load_dwordx4 v[114:117], v12, s[6:7] offset:2560
	ds_read_u16 v12, v226 offset:224
	s_waitcnt lgkmcnt(0)
	v_mad_u32_u24 v12, v12, s50, v203
	global_load_dwordx4 v[122:125], v12, s[6:7] offset:2560
	ds_read_u16 v12, v226 offset:240
	s_waitcnt lgkmcnt(0)
	v_mad_u32_u24 v12, v12, s50, v203
	global_load_dwordx4 v[126:129], v12, s[6:7] offset:2560
	s_waitcnt lgkmcnt(0)
	ds_read_b128 v[12:15], v10
	ds_read_b128 v[34:37], v11
	s_waitcnt lgkmcnt(1)
	v_mfma_f32_16x16x32_bf16 v[12:15], v[12:15], v[2:5], 0
	s_waitcnt lgkmcnt(0)
	v_mfma_f32_16x16x32_bf16 v[170:173], v[34:37], v[6:9], v[12:15]
	s_nop 5
	ds_read_b128 v[12:15], v10 offset:2048
	ds_read_b128 v[34:37], v11 offset:2048
	s_waitcnt lgkmcnt(1)
	v_mfma_f32_16x16x32_bf16 v[12:15], v[12:15], v[2:5], 0
	s_waitcnt lgkmcnt(0)
	v_mfma_f32_16x16x32_bf16 v[162:165], v[34:37], v[6:9], v[12:15]
	s_nop 5
	ds_read_b128 v[12:15], v10 offset:4096
	ds_read_b128 v[34:37], v11 offset:4096
	s_waitcnt lgkmcnt(1)
	v_mfma_f32_16x16x32_bf16 v[12:15], v[12:15], v[2:5], 0
	s_waitcnt lgkmcnt(0)
	v_mfma_f32_16x16x32_bf16 v[154:157], v[34:37], v[6:9], v[12:15]
	s_nop 5
	ds_read_b128 v[12:15], v10 offset:6144
	ds_read_b128 v[34:37], v11 offset:6144
	s_waitcnt lgkmcnt(1)
	v_mfma_f32_16x16x32_bf16 v[12:15], v[12:15], v[2:5], 0
	s_waitcnt lgkmcnt(0)
	v_mfma_f32_16x16x32_bf16 v[146:149], v[34:37], v[6:9], v[12:15]
	s_nop 5
	ds_read_b128 v[12:15], v10 offset:8192
	ds_read_b128 v[34:37], v11 offset:8192
	s_waitcnt lgkmcnt(1)
	v_mfma_f32_16x16x32_bf16 v[12:15], v[12:15], v[2:5], 0
	s_waitcnt lgkmcnt(0)
	v_mfma_f32_16x16x32_bf16 v[142:145], v[34:37], v[6:9], v[12:15]
	s_nop 5
	ds_read_b128 v[12:15], v10 offset:10240
	ds_read_b128 v[34:37], v11 offset:10240
	s_waitcnt lgkmcnt(1)
	v_mfma_f32_16x16x32_bf16 v[12:15], v[12:15], v[2:5], 0
	s_waitcnt lgkmcnt(0)
	v_mfma_f32_16x16x32_bf16 v[138:141], v[34:37], v[6:9], v[12:15]
	s_nop 5
	ds_read_b128 v[12:15], v10 offset:12288
	ds_read_b128 v[34:37], v11 offset:12288
	s_waitcnt lgkmcnt(1)
	v_mfma_f32_16x16x32_bf16 v[12:15], v[12:15], v[2:5], 0
	s_waitcnt lgkmcnt(0)
	v_mfma_f32_16x16x32_bf16 v[134:137], v[34:37], v[6:9], v[12:15]
	s_nop 5
	ds_read_b128 v[12:15], v10 offset:14336
	ds_read_b128 v[34:37], v11 offset:14336
	s_waitcnt lgkmcnt(0)
	s_waitcnt lgkmcnt(1)
	v_mfma_f32_16x16x32_bf16 v[2:5], v[12:15], v[2:5], 0
	s_waitcnt lgkmcnt(0)
	v_mfma_f32_16x16x32_bf16 v[130:133], v[34:37], v[6:9], v[2:5]
	s_nop 5
	ds_read_u16 v2, v226 offset:256
	ds_read_u16 v6, v226 offset:272
	ds_read_u16 v10, v226 offset:288
	ds_read_u16 v14, v226 offset:304
	ds_read_u16 v34, v226 offset:320
	ds_read_u16 v38, v226 offset:336
	ds_read_u16 v46, v226 offset:352
	ds_read_u16 v58, v226 offset:368
	ds_read_u16 v66, v226 offset:384
	ds_read_u16 v70, v226 offset:400
	ds_read_u16 v78, v226 offset:416
	ds_read_u16 v86, v226 offset:432
	ds_read_u16 v94, v226 offset:448
	ds_read_u16 v102, v226 offset:464
	ds_read_u16 v110, v226 offset:480
	ds_read_u16 v118, v226 offset:496
	v_lshlrev_b32_e32 v226, 2, v219
	s_waitcnt lgkmcnt(14)
	v_mad_u32_u24 v2, v2, s50, v203
	v_mad_u32_u24 v6, v6, s50, v203
	s_waitcnt lgkmcnt(13)
	v_mad_u32_u24 v10, v10, s50, v203
	s_waitcnt lgkmcnt(12)
	v_mad_u32_u24 v14, v14, s50, v203
	s_waitcnt lgkmcnt(11)
	v_mad_u32_u24 v34, v34, s50, v203
	s_waitcnt lgkmcnt(10)
	v_mad_u32_u24 v38, v38, s50, v203
	s_waitcnt lgkmcnt(9)
	v_mad_u32_u24 v46, v46, s50, v203
	s_waitcnt lgkmcnt(8)
	v_mad_u32_u24 v58, v58, s50, v203
	s_waitcnt lgkmcnt(7)
	v_mad_u32_u24 v66, v66, s50, v203
	s_waitcnt lgkmcnt(6)
	v_mad_u32_u24 v70, v70, s50, v203
	s_waitcnt lgkmcnt(5)
	v_mad_u32_u24 v78, v78, s50, v203
	s_waitcnt lgkmcnt(4)
	v_mad_u32_u24 v86, v86, s50, v203
	s_waitcnt lgkmcnt(3)
	v_mad_u32_u24 v94, v94, s50, v203
	s_waitcnt lgkmcnt(2)
	v_mad_u32_u24 v102, v102, s50, v203
	s_waitcnt lgkmcnt(1)
; #define LOADKV2(BASECOL, SH) { _Pragma("unroll") for (int rr = 0; rr < 16; ++rr) { \
;       const unsigned vo_ = (unsigned)mySel[(SH) * 128 + rr * 8 + (lane >> 3)] * 4608u + (unsigned)(hkv * 128 + (lane & 7) * 16); \
;       vreg2[rr] = *(const bf16x8*)((const char*)(Pb + (BASECOL)) + (size_t)vo_); } }
; DI void phase_mix_b2(int wv_, int vb_, int nvb_, char* ws_, const Ctx& p, char* smem) {
;     ...
;     LOADKV2(1280, 1)
;     ...
;     float mx = -INFINITY;
; #pragma unroll
;     for (int kb = 0; kb < 16; ++kb)
; #pragma unroll
;       for (int i = 0; i < 4; ++i) {
;         const unsigned bk4 = *(const unsigned*)(mySelb + kb * 16 + fq * 4);
;         const int bk = (bk4 >> (8 * i)) & 255;
;         const float bv = sbias[bk * 16 + hkv * 4 + (n16 & 3)];
;         const float v = lg[kb][i] + bv;
;         lg[kb][i] = v; mx = fmaxf(mx, v);
;       }
	v_mad_u32_u24 v110, v110, s50, v203
	s_waitcnt lgkmcnt(0)
	v_mad_u32_u24 v118, v118, s50, v203
	v_add_u32_e32 v229, v202, v226
	global_load_dwordx4 v[2:5], v2, s[6:7] offset:2560
	s_nop 0
	global_load_dwordx4 v[6:9], v6, s[6:7] offset:2560
	s_nop 0
	global_load_dwordx4 v[10:13], v10, s[6:7] offset:2560
	s_nop 0
	global_load_dwordx4 v[14:17], v14, s[6:7] offset:2560
	s_nop 0
	global_load_dwordx4 v[34:37], v34, s[6:7] offset:2560
	s_nop 0
	global_load_dwordx4 v[38:41], v38, s[6:7] offset:2560
	s_nop 0
	global_load_dwordx4 v[46:49], v46, s[6:7] offset:2560
	s_nop 0
	global_load_dwordx4 v[58:61], v58, s[6:7] offset:2560
	s_nop 0
	global_load_dwordx4 v[66:69], v66, s[6:7] offset:2560
	s_nop 0
	global_load_dwordx4 v[70:73], v70, s[6:7] offset:2560
	s_nop 0
	global_load_dwordx4 v[78:81], v78, s[6:7] offset:2560
	s_nop 0
	global_load_dwordx4 v[86:89], v86, s[6:7] offset:2560
	s_nop 0
	global_load_dwordx4 v[94:97], v94, s[6:7] offset:2560
	s_nop 0
	global_load_dwordx4 v[102:105], v102, s[6:7] offset:2560
	s_nop 0
	global_load_dwordx4 v[110:113], v110, s[6:7] offset:2560
	s_nop 0
	global_load_dwordx4 v[118:121], v118, s[6:7] offset:2560
	s_movk_i32 s6, 0x60
	v_add_u32_e32 v203, v216, v228
	ds_read2_b32 v[194:195], v229 offset1:4
	ds_read2_b32 v[196:197], v229 offset0:8 offset1:12
	ds_read2_b32 v[198:199], v229 offset0:16 offset1:20
	ds_read2_b32 v[230:231], v229 offset0:24 offset1:28
	s_waitcnt lgkmcnt(3)
	v_bfe_u32 v232, v194, 0, 8
	v_lshl_add_u32 v232, v232, 6, v203
	ds_read_b32 v232, v232
	v_bfe_u32 v233, v194, 16, 8
	v_lshl_add_u32 v233, v233, 6, v203
	ds_read_b32 v233, v233
	v_bfe_u32 v234, v194, 8, 8
	v_lshl_add_u32 v234, v234, 6, v203
	ds_read_b32 v234, v234
	v_bfe_u32 v235, v194, 24, 8
	v_lshl_add_u32 v235, v235, 6, v203
	ds_read_b32 v235, v235
	v_bfe_u32 v236, v195, 0, 8
	v_lshl_add_u32 v236, v236, 6, v203
	ds_read_b32 v236, v236
	v_bfe_u32 v237, v195, 8, 8
	v_lshl_add_u32 v237, v237, 6, v203
	ds_read_b32 v237, v237
	v_bfe_u32 v238, v195, 16, 8
	v_lshl_add_u32 v238, v238, 6, v203
	ds_read_b32 v238, v238
	v_bfe_u32 v239, v195, 24, 8
	v_lshl_add_u32 v239, v239, 6, v203
	ds_read_b32 v239, v239
	s_waitcnt lgkmcnt(10)
	v_bfe_u32 v240, v196, 0, 8
	v_lshl_add_u32 v240, v240, 6, v203
	ds_read_b32 v240, v240
	v_bfe_u32 v241, v196, 8, 8
	v_lshl_add_u32 v241, v241, 6, v203
	ds_read_b32 v241, v241
	v_bfe_u32 v246, v196, 16, 8
	v_lshl_add_u32 v246, v246, 6, v203
	ds_read_b32 v246, v246
	v_bfe_u32 v247, v196, 24, 8
	v_lshl_add_u32 v247, v247, 6, v203
	ds_read_b32 v247, v247
	v_bfe_u32 v248, v197, 0, 8
	v_lshl_add_u32 v248, v248, 6, v203
	ds_read_b32 v248, v248
	v_bfe_u32 v249, v197, 8, 8
	v_lshl_add_u32 v249, v249, 6, v203
	ds_read_b32 v249, v249
	v_bfe_u32 v250, v197, 16, 8
	v_lshl_add_u32 v250, v250, 6, v203
	ds_read_b32 v250, v250
	v_bfe_u32 v251, v197, 24, 8
	v_lshl_add_u32 v251, v251, 6, v203
	ds_read_b32 v251, v251
	s_waitcnt lgkmcnt(8)
	v_add_f32_e32 v190, v190, v232
	v_add_f32_e32 v192, v192, v233
	v_add_f32_e32 v191, v191, v234
	v_add_f32_e32 v193, v193, v235
	v_add_f32_e32 v227, v186, v236
	v_add_f32_e32 v186, v187, v237
	v_add_f32_e32 v187, v188, v238
	v_add_f32_e32 v188, v189, v239
	v_max3_f32 v209, v190, s39, v192
	v_max3_f32 v209, v209, v191, v193
	v_max3_f32 v209, v209, v227, v186
	v_max3_f32 v209, v209, v187, v188
	v_bfe_u32 v232, v198, 0, 8
	v_lshl_add_u32 v232, v232, 6, v203
	ds_read_b32 v232, v232
	v_bfe_u32 v233, v198, 8, 8
	v_lshl_add_u32 v233, v233, 6, v203
	ds_read_b32 v233, v233
	v_bfe_u32 v234, v198, 16, 8
	v_lshl_add_u32 v234, v234, 6, v203
	ds_read_b32 v234, v234
	v_bfe_u32 v235, v198, 24, 8
	v_lshl_add_u32 v235, v235, 6, v203
	ds_read_b32 v235, v235
	v_bfe_u32 v236, v199, 0, 8
	v_lshl_add_u32 v236, v236, 6, v203
	ds_read_b32 v236, v236
	v_bfe_u32 v237, v199, 8, 8
	v_lshl_add_u32 v237, v237, 6, v203
	ds_read_b32 v237, v237
	v_bfe_u32 v238, v199, 16, 8
	v_lshl_add_u32 v238, v238, 6, v203
	ds_read_b32 v238, v238
	v_bfe_u32 v239, v199, 24, 8
	v_lshl_add_u32 v239, v239, 6, v203
	ds_read_b32 v239, v239
	s_waitcnt lgkmcnt(8)
	v_add_f32_e32 v189, v182, v240
	v_add_f32_e32 v182, v183, v241
	v_add_f32_e32 v183, v184, v246
	v_add_f32_e32 v184, v185, v247
	v_add_f32_e32 v185, v178, v248
	v_add_f32_e32 v178, v179, v249
	v_add_f32_e32 v179, v180, v250
	v_add_f32_e32 v180, v181, v251
	v_max3_f32 v209, v209, v189, v182
	v_max3_f32 v209, v209, v183, v184
	v_max3_f32 v209, v209, v185, v178
	v_max3_f32 v209, v209, v179, v180
	v_bfe_u32 v240, v230, 0, 8
	v_lshl_add_u32 v240, v240, 6, v203
	ds_read_b32 v240, v240
	v_bfe_u32 v241, v230, 8, 8
	v_lshl_add_u32 v241, v241, 6, v203
	ds_read_b32 v241, v241
	v_bfe_u32 v246, v230, 16, 8
	v_lshl_add_u32 v246, v246, 6, v203
	ds_read_b32 v246, v246
	v_bfe_u32 v247, v230, 24, 8
	v_lshl_add_u32 v247, v247, 6, v203
	ds_read_b32 v247, v247
	v_bfe_u32 v248, v231, 0, 8
	v_lshl_add_u32 v248, v248, 6, v203
	ds_read_b32 v248, v248
	v_bfe_u32 v249, v231, 8, 8
	v_lshl_add_u32 v249, v249, 6, v203
	ds_read_b32 v249, v249
	v_bfe_u32 v250, v231, 16, 8
	v_lshl_add_u32 v250, v250, 6, v203
	ds_read_b32 v250, v250
	v_bfe_u32 v251, v231, 24, 8
	v_lshl_add_u32 v251, v251, 6, v203
	ds_read_b32 v251, v251
	s_waitcnt lgkmcnt(8)
	v_add_f32_e32 v181, v174, v232
	v_add_f32_e32 v174, v175, v233
	v_add_f32_e32 v175, v176, v234
	v_add_f32_e32 v176, v177, v235
	v_add_f32_e32 v177, v166, v236
	v_add_f32_e32 v166, v167, v237
	v_add_f32_e32 v167, v168, v238
	v_add_f32_e32 v168, v169, v239
	v_max3_f32 v209, v209, v181, v174
	v_max3_f32 v209, v209, v175, v176
	v_max3_f32 v209, v209, v177, v166
	v_max3_f32 v209, v209, v167, v168
	s_waitcnt lgkmcnt(0)
; DI float shx(float v, int m) { return __int_as_float(__builtin_amdgcn_ds_bpermute((lane_now() ^ m) << 2, __float_as_int(v))); }
; DI int shx(int v, int m) { return __builtin_amdgcn_ds_bpermute((lane_now() ^ m) << 2, v); }
; DI void phase_mix_b2(int wv_, int vb_, int nvb_, char* ws_, const Ctx& p, char* smem) {
;     ...
;     float mx = -INFINITY;
; #pragma unroll
;     for (int kb = 0; kb < 16; ++kb)
; #pragma unroll
;       for (int i = 0; i < 4; ++i) {
;         const unsigned bk4 = *(const unsigned*)(mySelb + kb * 16 + fq * 4);
;         const int bk = (bk4 >> (8 * i)) & 255;
;         const float bv = sbias[bk * 16 + hkv * 4 + (n16 & 3)];
;         const float v = lg[kb][i] + bv;
;         lg[kb][i] = v; mx = fmaxf(mx, v);
;       }
;     mx = fmaxf(mx, shx(mx, 16)); mx = fmaxf(mx, shx(mx, 32));
	v_add_f32_e32 v169, v158, v240
	v_add_f32_e32 v158, v159, v241
	v_add_f32_e32 v159, v160, v246
	v_add_f32_e32 v160, v161, v247
	v_add_f32_e32 v161, v150, v248
	v_add_f32_e32 v150, v151, v249
	v_add_f32_e32 v151, v152, v250
	v_add_f32_e32 v152, v153, v251
	v_max3_f32 v209, v209, v169, v158
	v_max3_f32 v209, v209, v159, v160
	v_max3_f32 v209, v209, v161, v150
	v_max3_f32 v209, v209, v151, v152
	ds_read2_b32 v[194:195], v229 offset0:32 offset1:36
	ds_read2_b32 v[196:197], v229 offset0:40 offset1:44
	ds_read2_b32 v[198:199], v229 offset0:48 offset1:52
	ds_read2_b32 v[230:231], v229 offset0:56 offset1:60
	s_waitcnt lgkmcnt(3)
	v_bfe_u32 v232, v194, 0, 8
	v_lshl_add_u32 v232, v232, 6, v203
	ds_read_b32 v232, v232
	v_bfe_u32 v233, v194, 8, 8
	v_lshl_add_u32 v233, v233, 6, v203
	ds_read_b32 v233, v233
	v_bfe_u32 v234, v194, 16, 8
	v_lshl_add_u32 v234, v234, 6, v203
	ds_read_b32 v234, v234
	v_bfe_u32 v235, v194, 24, 8
	v_lshl_add_u32 v235, v235, 6, v203
	ds_read_b32 v235, v235
	v_bfe_u32 v236, v195, 0, 8
	v_lshl_add_u32 v236, v236, 6, v203
	ds_read_b32 v236, v236
	v_bfe_u32 v237, v195, 8, 8
	v_lshl_add_u32 v237, v237, 6, v203
	ds_read_b32 v237, v237
	v_bfe_u32 v238, v195, 16, 8
	v_lshl_add_u32 v238, v238, 6, v203
	ds_read_b32 v238, v238
	v_bfe_u32 v239, v195, 24, 8
	v_lshl_add_u32 v239, v239, 6, v203
	ds_read_b32 v239, v239
	s_waitcnt lgkmcnt(10)
	v_bfe_u32 v240, v196, 0, 8
	v_lshl_add_u32 v240, v240, 6, v203
	ds_read_b32 v240, v240
	v_bfe_u32 v241, v196, 8, 8
	v_lshl_add_u32 v241, v241, 6, v203
	ds_read_b32 v241, v241
	v_bfe_u32 v246, v196, 16, 8
	v_lshl_add_u32 v246, v246, 6, v203
	ds_read_b32 v246, v246
	v_bfe_u32 v247, v196, 24, 8
	v_lshl_add_u32 v247, v247, 6, v203
	ds_read_b32 v247, v247
	v_bfe_u32 v248, v197, 0, 8
	v_lshl_add_u32 v248, v248, 6, v203
	ds_read_b32 v248, v248
	v_bfe_u32 v249, v197, 8, 8
	v_lshl_add_u32 v249, v249, 6, v203
	ds_read_b32 v249, v249
	v_bfe_u32 v250, v197, 16, 8
	v_lshl_add_u32 v250, v250, 6, v203
	ds_read_b32 v250, v250
	v_bfe_u32 v251, v197, 24, 8
	v_lshl_add_u32 v251, v251, 6, v203
	ds_read_b32 v251, v251
	s_waitcnt lgkmcnt(8)
	v_add_f32_e32 v170, v170, v232
	v_add_f32_e32 v153, v171, v233
	v_add_f32_e32 v171, v172, v234
	v_add_f32_e32 v172, v173, v235
	v_add_f32_e32 v173, v162, v236
	v_add_f32_e32 v162, v163, v237
	v_add_f32_e32 v163, v164, v238
	v_add_f32_e32 v164, v165, v239
	v_max3_f32 v209, v209, v170, v153
	v_max3_f32 v209, v209, v171, v172
	v_max3_f32 v209, v209, v173, v162
	v_max3_f32 v209, v209, v163, v164
	v_bfe_u32 v232, v198, 0, 8
	v_lshl_add_u32 v232, v232, 6, v203
	ds_read_b32 v232, v232
	v_bfe_u32 v233, v198, 8, 8
	v_lshl_add_u32 v233, v233, 6, v203
	ds_read_b32 v233, v233
	v_bfe_u32 v234, v198, 16, 8
	v_lshl_add_u32 v234, v234, 6, v203
	ds_read_b32 v234, v234
	v_bfe_u32 v235, v198, 24, 8
	v_lshl_add_u32 v235, v235, 6, v203
	ds_read_b32 v235, v235
	v_bfe_u32 v236, v199, 0, 8
	v_lshl_add_u32 v236, v236, 6, v203
	ds_read_b32 v236, v236
	v_bfe_u32 v237, v199, 8, 8
	v_lshl_add_u32 v237, v237, 6, v203
	ds_read_b32 v237, v237
	v_bfe_u32 v238, v199, 16, 8
	v_lshl_add_u32 v238, v238, 6, v203
	ds_read_b32 v238, v238
	v_bfe_u32 v239, v199, 24, 8
	v_lshl_add_u32 v239, v239, 6, v203
	ds_read_b32 v239, v239
	s_waitcnt lgkmcnt(8)
	v_add_f32_e32 v165, v154, v240
	v_add_f32_e32 v154, v155, v241
	v_add_f32_e32 v155, v156, v246
	v_add_f32_e32 v156, v157, v247
	v_add_f32_e32 v157, v146, v248
	v_add_f32_e32 v146, v147, v249
	v_add_f32_e32 v147, v148, v250
	v_add_f32_e32 v148, v149, v251
	v_max3_f32 v209, v209, v165, v154
	v_max3_f32 v209, v209, v155, v156
	v_max3_f32 v209, v209, v157, v146
	v_max3_f32 v209, v209, v147, v148
	v_bfe_u32 v240, v230, 0, 8
	v_lshl_add_u32 v240, v240, 6, v203
	ds_read_b32 v240, v240
	v_bfe_u32 v241, v230, 8, 8
	v_lshl_add_u32 v241, v241, 6, v203
	ds_read_b32 v241, v241
	v_bfe_u32 v246, v230, 16, 8
	v_lshl_add_u32 v246, v246, 6, v203
	ds_read_b32 v246, v246
	v_bfe_u32 v247, v230, 24, 8
	v_lshl_add_u32 v247, v247, 6, v203
	ds_read_b32 v247, v247
	v_bfe_u32 v248, v231, 0, 8
	v_lshl_add_u32 v248, v248, 6, v203
	ds_read_b32 v248, v248
	v_bfe_u32 v249, v231, 8, 8
	v_lshl_add_u32 v249, v249, 6, v203
	ds_read_b32 v249, v249
	v_bfe_u32 v250, v231, 16, 8
	v_lshl_add_u32 v250, v250, 6, v203
	ds_read_b32 v250, v250
	v_bfe_u32 v251, v231, 24, 8
	v_lshl_add_u32 v251, v251, 6, v203
	ds_read_b32 v251, v251
	s_waitcnt lgkmcnt(8)
	v_add_f32_e32 v149, v142, v232
	v_add_f32_e32 v142, v143, v233
	v_add_f32_e32 v143, v144, v234
	v_add_f32_e32 v144, v145, v235
	v_add_f32_e32 v138, v138, v236
	v_add_f32_e32 v139, v139, v237
	v_add_f32_e32 v140, v140, v238
	v_add_f32_e32 v141, v141, v239
	v_max3_f32 v209, v209, v149, v142
	v_max3_f32 v209, v209, v143, v144
	v_max3_f32 v209, v209, v138, v139
	v_max3_f32 v209, v209, v140, v141
	s_waitcnt lgkmcnt(0)
	v_add_f32_e32 v145, v134, v240
	v_add_f32_e32 v134, v135, v241
	v_add_f32_e32 v135, v136, v246
	v_add_f32_e32 v136, v137, v247
	v_add_f32_e32 v130, v130, v248
	v_add_f32_e32 v131, v131, v249
	v_add_f32_e32 v137, v132, v250
	v_add_f32_e32 v202, v133, v251
	v_max3_f32 v209, v209, v145, v134
	v_max3_f32 v209, v209, v135, v136
	v_max3_f32 v209, v209, v130, v131
	v_mov_b32_e32 v133, v204
	v_max3_f32 v132, v209, v137, v202
	v_lshlrev_b32_e32 v133, 2, v133
	v_xor_b32_e32 v133, 64, v133
	ds_bpermute_b32 v133, v133, v132
	s_waitcnt lgkmcnt(0)
	v_max_f32_e32 v133, v133, v133
	v_max_f32_e32 v132, v132, v133
	v_mov_b32_e32 v133, v204
	s_nop 0
	v_lshlrev_b32_e32 v133, 2, v133
	v_xor_b32_e32 v133, 0x80, v133
	ds_bpermute_b32 v133, v133, v132
	s_waitcnt lgkmcnt(0)
; DI float shx(float v, int m) { return __int_as_float(__builtin_amdgcn_ds_bpermute((lane_now() ^ m) << 2, __float_as_int(v))); }
; DI int shx(int v, int m) { return __builtin_amdgcn_ds_bpermute((lane_now() ^ m) << 2, v); }
; DI u16 f2bf(float x) { return (u16)(pk2bf(x, 0.f) & 0xffffu); }
; DI void phase_mix_b2(int wv_, int vb_, int nvb_, char* ws_, const Ctx& p, char* smem) {
;     ...
;     float sum = 0.f;
; #pragma unroll
;     for (int kb = 0; kb < 16; ++kb)
; #pragma unroll
;       for (int i = 0; i < 4; ++i) { float pv = __builtin_amdgcn_exp2f(lg[kb][i] - mx); lg[kb][i] = pv; sum += pv; }
;     sum += shx(sum, 16); sum += shx(sum, 32);
;     bf16x8 pall[8];
; #pragma unroll
;     for (int q = 0; q < 8; ++q)
; #pragma unroll
;       for (int j = 0; j < 4; ++j) { pall[q][j] = (short)f2bf(lg[2 * q][j]); pall[q][4 + j] = (short)f2bf(lg[2 * q + 1][j]); }
	v_max_f32_e32 v133, v133, v133
	v_max_f32_e32 v203, v132, v133
	v_sub_f32_e32 v132, v190, v203
	v_exp_f32_e32 v132, v132
	v_sub_f32_e32 v133, v191, v203
	v_exp_f32_e32 v133, v133
	v_sub_f32_e32 v186, v186, v203
	v_add_f32_e32 v190, 0, v132
	v_exp_f32_e32 v186, v186
	v_add_f32_e32 v191, v133, v190
	v_sub_f32_e32 v190, v192, v203
	v_exp_f32_e32 v190, v190
	v_sub_f32_e32 v187, v187, v203
	v_exp_f32_e32 v187, v187
	v_sub_f32_e32 v188, v188, v203
	v_add_f32_e32 v192, v190, v191
	v_sub_f32_e32 v191, v193, v203
	v_exp_f32_e32 v191, v191
	v_sub_f32_e32 v182, v182, v203
	v_exp_f32_e32 v182, v182
	v_sub_f32_e32 v183, v183, v203
	v_add_f32_e32 v193, v191, v192
	v_sub_f32_e32 v192, v227, v203
	v_exp_f32_e32 v192, v192
	v_exp_f32_e32 v183, v183
	v_sub_f32_e32 v184, v184, v203
	v_exp_f32_e32 v184, v184
	v_add_f32_e32 v193, v192, v193
	v_add_f32_e32 v193, v186, v193
	v_add_f32_e32 v194, v187, v193
	v_exp_f32_e32 v193, v188
	v_sub_f32_e32 v188, v189, v203
	v_exp_f32_e32 v188, v188
	v_sub_f32_e32 v185, v185, v203
	v_add_f32_e32 v194, v193, v194
	v_exp_f32_e32 v185, v185
	v_add_f32_e32 v189, v188, v194
	v_sub_f32_e32 v178, v178, v203
	v_add_f32_e32 v189, v182, v189
	v_exp_f32_e32 v178, v178
	v_sub_f32_e32 v179, v179, v203
	v_add_f32_e32 v189, v183, v189
	v_exp_f32_e32 v179, v179
	v_sub_f32_e32 v180, v180, v203
	v_add_f32_e32 v189, v184, v189
	v_exp_f32_e32 v180, v180
	v_sub_f32_e32 v181, v181, v203
	v_add_f32_e32 v189, v185, v189
	v_exp_f32_e32 v181, v181
	v_sub_f32_e32 v174, v174, v203
	v_add_f32_e32 v189, v178, v189
	v_exp_f32_e32 v174, v174
	v_sub_f32_e32 v175, v175, v203
	v_add_f32_e32 v189, v179, v189
	v_exp_f32_e32 v175, v175
	v_sub_f32_e32 v176, v176, v203
	v_add_f32_e32 v189, v180, v189
	v_exp_f32_e32 v176, v176
	v_sub_f32_e32 v177, v177, v203
	v_add_f32_e32 v189, v181, v189
	v_exp_f32_e32 v177, v177
	v_sub_f32_e32 v166, v166, v203
	v_add_f32_e32 v189, v174, v189
	v_exp_f32_e32 v166, v166
	v_sub_f32_e32 v167, v167, v203
	v_add_f32_e32 v189, v175, v189
	v_exp_f32_e32 v167, v167
	v_sub_f32_e32 v168, v168, v203
	v_add_f32_e32 v189, v176, v189
	v_exp_f32_e32 v168, v168
	v_sub_f32_e32 v169, v169, v203
	v_add_f32_e32 v189, v177, v189
	v_exp_f32_e32 v169, v169
	v_sub_f32_e32 v158, v158, v203
	v_add_f32_e32 v189, v166, v189
	v_exp_f32_e32 v194, v158
	v_add_f32_e32 v189, v167, v189
	v_add_f32_e32 v189, v168, v189
	v_add_f32_e32 v189, v169, v189
	v_sub_f32_e32 v159, v159, v203
	v_add_f32_e32 v158, v194, v189
	v_exp_f32_e32 v189, v159
	v_sub_f32_e32 v159, v160, v203
	v_exp_f32_e32 v195, v159
	v_sub_f32_e32 v159, v161, v203
	v_exp_f32_e32 v196, v159
	v_sub_f32_e32 v150, v150, v203
	v_exp_f32_e32 v197, v150
	v_sub_f32_e32 v151, v151, v203
	v_add_f32_e32 v158, v189, v158
	v_exp_f32_e32 v198, v151
	v_sub_f32_e32 v151, v152, v203
	v_add_f32_e32 v158, v195, v158
	v_exp_f32_e32 v199, v151
	v_sub_f32_e32 v151, v170, v203
	v_add_f32_e32 v158, v196, v158
	v_exp_f32_e32 v170, v151
	v_sub_f32_e32 v151, v153, v203
	v_add_f32_e32 v150, v197, v158
	v_exp_f32_e32 v227, v151
	v_sub_f32_e32 v151, v171, v203
	v_add_f32_e32 v150, v198, v150
	v_exp_f32_e32 v171, v151
	v_sub_f32_e32 v151, v172, v203
	v_add_f32_e32 v150, v199, v150
	v_exp_f32_e32 v172, v151
	v_sub_f32_e32 v151, v173, v203
	v_add_f32_e32 v150, v170, v150
	v_exp_f32_e32 v173, v151
	v_sub_f32_e32 v151, v162, v203
	v_add_f32_e32 v150, v227, v150
	v_exp_f32_e32 v162, v151
	v_sub_f32_e32 v151, v163, v203
	v_add_f32_e32 v150, v171, v150
	v_exp_f32_e32 v163, v151
	v_sub_f32_e32 v151, v164, v203
	v_add_f32_e32 v150, v172, v150
	v_exp_f32_e32 v164, v151
	v_sub_f32_e32 v151, v165, v203
	v_add_f32_e32 v150, v173, v150
	v_exp_f32_e32 v165, v151
	v_sub_f32_e32 v151, v154, v203
	v_add_f32_e32 v150, v162, v150
	v_exp_f32_e32 v228, v151
	v_sub_f32_e32 v151, v155, v203
	v_add_f32_e32 v150, v163, v150
	v_exp_f32_e32 v229, v151
	v_sub_f32_e32 v151, v156, v203
	v_add_f32_e32 v150, v164, v150
	v_exp_f32_e32 v230, v151
	v_sub_f32_e32 v151, v157, v203
	v_add_f32_e32 v150, v165, v150
	v_exp_f32_e32 v231, v151
	v_sub_f32_e32 v146, v146, v203
	v_add_f32_e32 v150, v228, v150
	v_exp_f32_e32 v232, v146
	v_sub_f32_e32 v147, v147, v203
	v_add_f32_e32 v150, v229, v150
	v_exp_f32_e32 v233, v147
	v_sub_f32_e32 v147, v148, v203
	v_add_f32_e32 v150, v230, v150
	v_exp_f32_e32 v234, v147
	v_sub_f32_e32 v147, v149, v203
	v_add_f32_e32 v150, v231, v150
	v_exp_f32_e32 v235, v147
	v_sub_f32_e32 v142, v142, v203
	v_add_f32_e32 v146, v232, v150
	v_exp_f32_e32 v236, v142
	v_sub_f32_e32 v143, v143, v203
	v_add_f32_e32 v146, v233, v146
	v_exp_f32_e32 v237, v143
	v_sub_f32_e32 v143, v144, v203
	v_add_f32_e32 v146, v234, v146
	v_exp_f32_e32 v238, v143
	v_sub_f32_e32 v138, v138, v203
	v_add_f32_e32 v146, v235, v146
	v_exp_f32_e32 v239, v138
	v_sub_f32_e32 v139, v139, v203
	v_add_f32_e32 v142, v236, v146
	v_exp_f32_e32 v240, v139
	v_sub_f32_e32 v139, v140, v203
	v_add_f32_e32 v142, v237, v142
	v_exp_f32_e32 v241, v139
	v_sub_f32_e32 v139, v141, v203
	v_add_f32_e32 v142, v238, v142
	v_exp_f32_e32 v246, v139
	v_sub_f32_e32 v139, v145, v203
	v_add_f32_e32 v138, v239, v142
	v_exp_f32_e32 v247, v139
	v_sub_f32_e32 v134, v134, v203
	v_add_f32_e32 v138, v240, v138
	v_exp_f32_e32 v248, v134
	v_sub_f32_e32 v135, v135, v203
	v_add_f32_e32 v138, v241, v138
	v_exp_f32_e32 v249, v135
	v_sub_f32_e32 v135, v136, v203
	v_add_f32_e32 v138, v246, v138
	v_exp_f32_e32 v250, v135
	v_sub_f32_e32 v130, v130, v203
	v_add_f32_e32 v138, v247, v138
	v_exp_f32_e32 v130, v130
	v_sub_f32_e32 v131, v131, v203
	v_add_f32_e32 v134, v248, v138
	v_exp_f32_e32 v131, v131
	v_sub_f32_e32 v135, v137, v203
	v_add_f32_e32 v134, v249, v134
	v_exp_f32_e32 v251, v135
	v_sub_f32_e32 v135, v202, v203
	v_add_f32_e32 v134, v250, v134
	v_exp_f32_e32 v202, v135
	v_add_f32_e32 v134, v130, v134
	v_mov_b32_e32 v135, v204
	v_add_f32_e32 v134, v131, v134
	v_add_f32_e32 v134, v251, v134
	v_lshlrev_b32_e32 v135, 2, v135
	v_add_f32_e32 v134, v202, v134
	v_xor_b32_e32 v135, 64, v135
	ds_bpermute_b32 v135, v135, v134
	v_cvt_pk_bf16_f32 v144, v173, v162
	v_cvt_pk_bf16_f32 v145, v163, v164
	v_cvt_pk_bf16_f32 v138, v165, v228
	v_and_b32_e32 v165, 16, v224
	s_waitcnt lgkmcnt(0)
; #define MFMA16(a, b, c) __builtin_amdgcn_mfma_f32_16x16x32_bf16((a), (b), (c), 0, 0, 0)
; DI float shx(float v, int m) { return __int_as_float(__builtin_amdgcn_ds_bpermute((lane_now() ^ m) << 2, __float_as_int(v))); }
; DI int shx(int v, int m) { return __builtin_amdgcn_ds_bpermute((lane_now() ^ m) << 2, v); }
; DI float shidx(float v, int src) { return __int_as_float(__builtin_amdgcn_ds_bpermute(src << 2, __float_as_int(v))); }
; DI int shidx(int v, int src) { return __builtin_amdgcn_ds_bpermute(src << 2, v); }
; DI u16 f2bf(float x) { return (u16)(pk2bf(x, 0.f) & 0xffffu); }
; DI void phase_mix_b2(int wv_, int vb_, int nvb_, char* ws_, const Ctx& p, char* smem) {
;     ...
;     sum += shx(sum, 16); sum += shx(sum, 32);
;     bf16x8 pall[8];
; #pragma unroll
;     for (int q = 0; q < 8; ++q)
; #pragma unroll
;       for (int j = 0; j < 4; ++j) { pall[q][j] = (short)f2bf(lg[2 * q][j]); pall[q][4 + j] = (short)f2bf(lg[2 * q + 1][j]); }
;     char* Vs = smem + wave * 16384;
;     float invs[4];
; #pragma unroll
;     for (int i = 0; i < 4; ++i) invs[i] = 1.0f / shidx(sum, i);
;     f32x4 oacc[4];
; #pragma unroll
;     for (int cb = 0; cb < 4; ++cb) oacc[cb] = (f32x4){0.f, 0.f, 0.f, 0.f};
; #pragma unroll
;     for (int sh = 0; sh < 2; ++sh) {
;       asm volatile("s_waitcnt lgkmcnt(0)" ::: "memory");
; #pragma unroll
;       for (int rr = 0; rr < 16; ++rr) {
;         const int row = rr * 8 + (lane >> 3), piece = lane & 7;
;         *(bf16x8*)(Vs + row * 128 + (((piece >> 1) ^ ((row >> 1) & 3)) * 32) + (piece & 1) * 16) = (sh == 0) ? vreg[rr] : vreg2[rr];
;       }
;       asm volatile("s_waitcnt lgkmcnt(0)" ::: "memory");
; #pragma unroll
;       for (int ks = 0; ks < 4; ++ks) {
;         const bf16x8 pa = pall[sh * 4 + ks];
;         const int rlo = ks * 32 + fq * 4 + (n16 >> 2);
;         const int sw = (rlo >> 1) & 3;
; #pragma unroll
;         for (int cb = 0; cb < 4; ++cb) {
;           const int off = ((cb ^ sw) * 32) + (n16 & 3) * 8;
;           s16x4 lo = __builtin_amdgcn_ds_read_tr16_b64_v4i16((__attribute__((address_space(3))) s16x4*)(Vs + rlo * 128 + off));
;           s16x4 hi = __builtin_amdgcn_ds_read_tr16_b64_v4i16((__attribute__((address_space(3))) s16x4*)(Vs + (16 + rlo) * 128 + off));
;           bf16x8 vb = __builtin_shufflevector(lo, hi, 0, 1, 2, 3, 4, 5, 6, 7);
;           oacc[cb] = MFMA16(pa, vb, oacc[cb]);
;         }
;       }
;     }
	v_add_f32_e32 v203, v134, v135
	v_mov_b32_e32 v134, v204
	v_cvt_pk_bf16_f32 v153, v167, v168
	v_lshlrev_b32_e32 v134, 2, v134
	v_xor_b32_e32 v134, 0x80, v134
	ds_bpermute_b32 v209, v134, v203
	v_cvt_pk_bf16_f32 v152, v177, v166
	v_and_b32_e32 v166, 3, v204
	v_lshlrev_b32_e32 v166, 3, v166
	s_waitcnt lgkmcnt(0)
	v_cvt_pk_bf16_f32 v161, v187, v193
	s_waitcnt lgkmcnt(0)
	v_add_f32_e32 v162, v203, v209
	v_cvt_pk_bf16_f32 v160, v192, v186
	v_readlane_b32 s0, v162, 0
	v_readlane_b32 s1, v162, 1
	v_readlane_b32 s8, v162, 2
	v_readlane_b32 s9, v162, 3
	v_lshlrev_b32_e32 v162, 4, v204
	v_and_b32_e32 v163, 0x380, v162
	v_lshrrev_b32_e32 v162, 1, v204
	v_xor_b32_e32 v162, v223, v162
	v_lshlrev_b32_e32 v162, 5, v162
	v_and_b32_e32 v162, 0x60, v162
	v_add_u32_e32 v164, v225, v162
	v_lshrrev_b32_e32 v162, 2, v0
	v_or_b32_e32 v162, v226, v162
	v_lshl_add_u32 v167, v162, 7, v225
	v_lshlrev_b32_e32 v162, 4, v162
	v_add3_u32 v163, v164, v165, v163
	v_and_or_b32 v166, v162, s6, v166
	s_waitcnt vmcnt(31)
	ds_write_b128 v163, v[18:21]
	s_waitcnt vmcnt(30)
	ds_write_b128 v163, v[22:25] offset:1024
	s_waitcnt vmcnt(29)
	ds_write_b128 v163, v[26:29] offset:2048
	s_waitcnt vmcnt(28)
	ds_write_b128 v163, v[30:33] offset:3072
	s_waitcnt vmcnt(27)
	ds_write_b128 v163, v[42:45] offset:4096
	s_waitcnt vmcnt(26)
	ds_write_b128 v163, v[50:53] offset:5120
	s_waitcnt vmcnt(25)
	ds_write_b128 v163, v[54:57] offset:6144
	s_waitcnt vmcnt(24)
	ds_write_b128 v163, v[62:65] offset:7168
	s_waitcnt vmcnt(23)
	ds_write_b128 v163, v[74:77] offset:8192
	s_waitcnt vmcnt(22)
	ds_write_b128 v163, v[82:85] offset:9216
	s_waitcnt vmcnt(21)
	ds_write_b128 v163, v[90:93] offset:10240
	s_waitcnt vmcnt(20)
	ds_write_b128 v163, v[98:101] offset:11264
	s_waitcnt vmcnt(19)
	ds_write_b128 v163, v[106:109] offset:12288
	s_waitcnt vmcnt(18)
	ds_write_b128 v163, v[114:117] offset:13312
	s_waitcnt vmcnt(17)
	ds_write_b128 v163, v[122:125] offset:14336
	s_waitcnt vmcnt(16)
	ds_write_b128 v163, v[126:129] offset:15360
	v_add_u32_e32 v162, v167, v166
	s_waitcnt lgkmcnt(0)
	v_cvt_pk_bf16_f32 v159, v190, v191
	v_cvt_pk_bf16_f32 v158, v132, v133
	ds_read_b64_tr_b16 v[18:19], v162
	ds_read_b64_tr_b16 v[20:21], v162 offset:2048
	s_waitcnt lgkmcnt(0)
	v_mfma_f32_16x16x32_bf16 v[22:25], v[158:161], v[18:21], 0
	v_xad_u32 v20, v166, 32, v167
	v_xad_u32 v19, v166, 64, v167
	v_xad_u32 v18, v166, s6, v167
	v_cvt_pk_bf16_f32 v157, v179, v180
	v_cvt_pk_bf16_f32 v156, v185, v178
	v_cvt_pk_bf16_f32 v155, v183, v184
	v_cvt_pk_bf16_f32 v154, v188, v182
	ds_read_b64_tr_b16 v[26:27], v20
	ds_read_b64_tr_b16 v[28:29], v20 offset:2048
	ds_read_b64_tr_b16 v[30:31], v19
	ds_read_b64_tr_b16 v[32:33], v19 offset:2048
	ds_read_b64_tr_b16 v[42:43], v18
	ds_read_b64_tr_b16 v[44:45], v18 offset:2048
	ds_read_b64_tr_b16 v[50:51], v162 offset:4096
	ds_read_b64_tr_b16 v[52:53], v162 offset:6144
	s_waitcnt lgkmcnt(0)
	v_mfma_f32_16x16x32_bf16 v[22:25], v[154:157], v[50:53], v[22:25]
	ds_read_b64_tr_b16 v[50:51], v20 offset:4096
	ds_read_b64_tr_b16 v[52:53], v20 offset:6144
	v_cvt_pk_bf16_f32 v151, v175, v176
	v_cvt_pk_bf16_f32 v150, v181, v174
	v_mfma_f32_16x16x32_bf16 v[26:29], v[158:161], v[26:29], 0
	v_cvt_pk_bf16_f32 v149, v198, v199
	v_cvt_pk_bf16_f32 v148, v196, v197
	v_cvt_pk_bf16_f32 v147, v189, v195
	s_waitcnt lgkmcnt(0)
	v_mfma_f32_16x16x32_bf16 v[26:29], v[154:157], v[50:53], v[26:29]
	ds_read_b64_tr_b16 v[50:51], v19 offset:4096
	ds_read_b64_tr_b16 v[52:53], v19 offset:6144
	v_cvt_pk_bf16_f32 v146, v169, v194
	v_cvt_pk_bf16_f32 v143, v171, v172
	v_mfma_f32_16x16x32_bf16 v[30:33], v[158:161], v[30:33], 0
	v_cvt_pk_bf16_f32 v142, v170, v227
	v_cvt_pk_bf16_f32 v141, v233, v234
	v_cvt_pk_bf16_f32 v140, v231, v232
	s_waitcnt lgkmcnt(0)
	v_mfma_f32_16x16x32_bf16 v[30:33], v[154:157], v[50:53], v[30:33]
	ds_read_b64_tr_b16 v[50:51], v18 offset:4096
	ds_read_b64_tr_b16 v[52:53], v18 offset:6144
	v_cvt_pk_bf16_f32 v139, v229, v230
	v_cvt_pk_bf16_f32 v137, v241, v246
	v_mfma_f32_16x16x32_bf16 v[42:45], v[158:161], v[42:45], 0
	v_cvt_pk_bf16_f32 v136, v239, v240
	v_cvt_pk_bf16_f32 v135, v237, v238
	v_cvt_pk_bf16_f32 v134, v235, v236
	s_waitcnt lgkmcnt(0)
	v_mfma_f32_16x16x32_bf16 v[42:45], v[154:157], v[50:53], v[42:45]
	ds_read_b64_tr_b16 v[50:51], v162 offset:8192
	ds_read_b64_tr_b16 v[52:53], v162 offset:10240
	v_cvt_pk_bf16_f32 v133, v251, v202
	v_cvt_pk_bf16_f32 v132, v130, v131
	s_waitcnt lgkmcnt(0)
	v_mfma_f32_16x16x32_bf16 v[22:25], v[150:153], v[50:53], v[22:25]
	ds_read_b64_tr_b16 v[50:51], v20 offset:8192
	ds_read_b64_tr_b16 v[52:53], v20 offset:10240
	v_cvt_pk_bf16_f32 v131, v249, v250
	v_cvt_pk_bf16_f32 v130, v247, v248
	s_waitcnt lgkmcnt(0)
	v_mfma_f32_16x16x32_bf16 v[26:29], v[150:153], v[50:53], v[26:29]
	ds_read_b64_tr_b16 v[50:51], v19 offset:8192
	ds_read_b64_tr_b16 v[52:53], v19 offset:10240
	s_waitcnt lgkmcnt(0)
	v_mfma_f32_16x16x32_bf16 v[30:33], v[150:153], v[50:53], v[30:33]
	ds_read_b64_tr_b16 v[50:51], v18 offset:8192
	ds_read_b64_tr_b16 v[52:53], v18 offset:10240
	s_waitcnt lgkmcnt(0)
	v_mfma_f32_16x16x32_bf16 v[42:45], v[150:153], v[50:53], v[42:45]
	ds_read_b64_tr_b16 v[50:51], v162 offset:12288
	ds_read_b64_tr_b16 v[52:53], v162 offset:14336
	s_waitcnt lgkmcnt(0)
	v_mfma_f32_16x16x32_bf16 v[22:25], v[146:149], v[50:53], v[22:25]
	ds_read_b64_tr_b16 v[50:51], v20 offset:12288
	ds_read_b64_tr_b16 v[52:53], v20 offset:14336
	s_waitcnt lgkmcnt(0)
	v_mfma_f32_16x16x32_bf16 v[26:29], v[146:149], v[50:53], v[26:29]
	ds_read_b64_tr_b16 v[50:51], v19 offset:12288
	ds_read_b64_tr_b16 v[52:53], v19 offset:14336
	s_waitcnt lgkmcnt(0)
; #define MFMA16(a, b, c) __builtin_amdgcn_mfma_f32_16x16x32_bf16((a), (b), (c), 0, 0, 0)
; DI void phase_mix_b2(int wv_, int vb_, int nvb_, char* ws_, const Ctx& p, char* smem) {
;     ...
; #pragma unroll
;     for (int sh = 0; sh < 2; ++sh) {
;       asm volatile("s_waitcnt lgkmcnt(0)" ::: "memory");
; #pragma unroll
;       for (int rr = 0; rr < 16; ++rr) {
;         const int row = rr * 8 + (lane >> 3), piece = lane & 7;
;         *(bf16x8*)(Vs + row * 128 + (((piece >> 1) ^ ((row >> 1) & 3)) * 32) + (piece & 1) * 16) = (sh == 0) ? vreg[rr] : vreg2[rr];
;       }
;       asm volatile("s_waitcnt lgkmcnt(0)" ::: "memory");
; #pragma unroll
;       for (int ks = 0; ks < 4; ++ks) {
;         const bf16x8 pa = pall[sh * 4 + ks];
;         const int rlo = ks * 32 + fq * 4 + (n16 >> 2);
;         const int sw = (rlo >> 1) & 3;
; #pragma unroll
;         for (int cb = 0; cb < 4; ++cb) {
;           const int off = ((cb ^ sw) * 32) + (n16 & 3) * 8;
;           s16x4 lo = __builtin_amdgcn_ds_read_tr16_b64_v4i16((__attribute__((address_space(3))) s16x4*)(Vs + rlo * 128 + off));
;           s16x4 hi = __builtin_amdgcn_ds_read_tr16_b64_v4i16((__attribute__((address_space(3))) s16x4*)(Vs + (16 + rlo) * 128 + off));
;           bf16x8 vb = __builtin_shufflevector(lo, hi, 0, 1, 2, 3, 4, 5, 6, 7);
;           oacc[cb] = MFMA16(pa, vb, oacc[cb]);
;         }
;       }
;     }
;     ...
;     if (fq == 0) {
	v_mfma_f32_16x16x32_bf16 v[30:33], v[146:149], v[50:53], v[30:33]
	ds_read_b64_tr_b16 v[50:51], v18 offset:12288
	ds_read_b64_tr_b16 v[52:53], v18 offset:14336
	s_waitcnt lgkmcnt(0)
	s_waitcnt vmcnt(15)
	ds_write_b128 v163, v[2:5]
	s_waitcnt vmcnt(14)
	ds_write_b128 v163, v[6:9] offset:1024
	s_waitcnt vmcnt(13)
	ds_write_b128 v163, v[10:13] offset:2048
	s_waitcnt vmcnt(12)
	ds_write_b128 v163, v[14:17] offset:3072
	s_waitcnt vmcnt(11)
	ds_write_b128 v163, v[34:37] offset:4096
	s_waitcnt vmcnt(10)
	ds_write_b128 v163, v[38:41] offset:5120
	s_waitcnt vmcnt(9)
	ds_write_b128 v163, v[46:49] offset:6144
	s_waitcnt vmcnt(8)
	ds_write_b128 v163, v[58:61] offset:7168
	s_waitcnt vmcnt(7)
	ds_write_b128 v163, v[66:69] offset:8192
	s_waitcnt vmcnt(6)
	ds_write_b128 v163, v[70:73] offset:9216
	s_waitcnt vmcnt(5)
	ds_write_b128 v163, v[78:81] offset:10240
	s_waitcnt vmcnt(4)
	ds_write_b128 v163, v[86:89] offset:11264
	s_waitcnt vmcnt(3)
	ds_write_b128 v163, v[94:97] offset:12288
	s_waitcnt vmcnt(2)
	ds_write_b128 v163, v[102:105] offset:13312
	s_waitcnt vmcnt(1)
	ds_write_b128 v163, v[110:113] offset:14336
	s_waitcnt vmcnt(0)
	ds_write_b128 v163, v[118:121] offset:15360
	s_waitcnt lgkmcnt(0)
	ds_read_b64_tr_b16 v[2:3], v162
	ds_read_b64_tr_b16 v[4:5], v162 offset:2048
	s_waitcnt lgkmcnt(0)
	v_mfma_f32_16x16x32_bf16 v[2:5], v[142:145], v[2:5], v[22:25]
	ds_read_b64_tr_b16 v[6:7], v20
	ds_read_b64_tr_b16 v[8:9], v20 offset:2048
	ds_read_b64_tr_b16 v[10:11], v19
	ds_read_b64_tr_b16 v[12:13], v19 offset:2048
	ds_read_b64_tr_b16 v[14:15], v18
	ds_read_b64_tr_b16 v[16:17], v18 offset:2048
	ds_read_b64_tr_b16 v[22:23], v162 offset:4096
	ds_read_b64_tr_b16 v[24:25], v162 offset:6144
	s_waitcnt lgkmcnt(0)
	v_mfma_f32_16x16x32_bf16 v[2:5], v[138:141], v[22:25], v[2:5]
	ds_read_b64_tr_b16 v[22:23], v20 offset:4096
	ds_read_b64_tr_b16 v[24:25], v20 offset:6144
	v_mfma_f32_16x16x32_bf16 v[6:9], v[142:145], v[6:9], v[26:29]
	s_waitcnt lgkmcnt(0)
	v_mfma_f32_16x16x32_bf16 v[6:9], v[138:141], v[22:25], v[6:9]
	ds_read_b64_tr_b16 v[22:23], v19 offset:4096
	ds_read_b64_tr_b16 v[24:25], v19 offset:6144
	v_mfma_f32_16x16x32_bf16 v[10:13], v[142:145], v[10:13], v[30:33]
	v_mfma_f32_16x16x32_bf16 v[42:45], v[146:149], v[50:53], v[42:45]
	s_waitcnt lgkmcnt(0)
	v_mfma_f32_16x16x32_bf16 v[10:13], v[138:141], v[22:25], v[10:13]
	ds_read_b64_tr_b16 v[22:23], v18 offset:4096
	ds_read_b64_tr_b16 v[24:25], v18 offset:6144
	v_mfma_f32_16x16x32_bf16 v[14:17], v[142:145], v[14:17], v[42:45]
	s_waitcnt lgkmcnt(0)
	v_mfma_f32_16x16x32_bf16 v[14:17], v[138:141], v[22:25], v[14:17]
	ds_read_b64_tr_b16 v[22:23], v162 offset:8192
	ds_read_b64_tr_b16 v[24:25], v162 offset:10240
	s_waitcnt lgkmcnt(0)
	v_mfma_f32_16x16x32_bf16 v[2:5], v[134:137], v[22:25], v[2:5]
	ds_read_b64_tr_b16 v[22:23], v20 offset:8192
	ds_read_b64_tr_b16 v[24:25], v20 offset:10240
	s_waitcnt lgkmcnt(0)
	v_mfma_f32_16x16x32_bf16 v[6:9], v[134:137], v[22:25], v[6:9]
	ds_read_b64_tr_b16 v[22:23], v19 offset:8192
	ds_read_b64_tr_b16 v[24:25], v19 offset:10240
	s_waitcnt lgkmcnt(0)
	v_mfma_f32_16x16x32_bf16 v[10:13], v[134:137], v[22:25], v[10:13]
	ds_read_b64_tr_b16 v[22:23], v18 offset:8192
	ds_read_b64_tr_b16 v[24:25], v18 offset:10240
	s_waitcnt lgkmcnt(0)
	v_mfma_f32_16x16x32_bf16 v[14:17], v[134:137], v[22:25], v[14:17]
	ds_read_b64_tr_b16 v[22:23], v162 offset:12288
	ds_read_b64_tr_b16 v[24:25], v162 offset:14336
	s_waitcnt lgkmcnt(0)
	v_mfma_f32_16x16x32_bf16 v[2:5], v[130:133], v[22:25], v[2:5]
	ds_read_b64_tr_b16 v[22:23], v20 offset:12288
	ds_read_b64_tr_b16 v[24:25], v20 offset:14336
	s_waitcnt lgkmcnt(0)
	v_mfma_f32_16x16x32_bf16 v[6:9], v[130:133], v[22:25], v[6:9]
	ds_read_b64_tr_b16 v[20:21], v19 offset:12288
	ds_read_b64_tr_b16 v[22:23], v19 offset:14336
	s_waitcnt lgkmcnt(0)
	v_mfma_f32_16x16x32_bf16 v[10:13], v[130:133], v[20:23], v[10:13]
	ds_read_b64_tr_b16 v[20:21], v18 offset:12288
	ds_read_b64_tr_b16 v[22:23], v18 offset:14336
	s_waitcnt lgkmcnt(0)
	v_mfma_f32_16x16x32_bf16 v[14:17], v[130:133], v[20:23], v[14:17]
	s_and_saveexec_b64 s[6:7], vcc
	s_cbranch_execz .LBB0_352
; DI float shidx(float v, int src) { return __int_as_float(__builtin_amdgcn_ds_bpermute(src << 2, __float_as_int(v))); }
; DI int shidx(int v, int src) { return __builtin_amdgcn_ds_bpermute(src << 2, v); }
; DI u16 f2bf(float x) { return (u16)(pk2bf(x, 0.f) & 0xffffu); }
; DI void phase_mix_b2(int wv_, int vb_, int nvb_, char* ws_, const Ctx& p, char* smem) {
;     ...
;     float invs[4];
; #pragma unroll
;     for (int i = 0; i < 4; ++i) invs[i] = 1.0f / shidx(sum, i);
;     ...
;     if (fq == 0) {
;       u16* yp = Y + qrow * 1024 + hkv * 256;
; #pragma unroll
;       for (int i = 0; i < 4; ++i)
; #pragma unroll
;         for (int cb = 0; cb < 4; ++cb) yp[i * 64 + cb * 16 + n16] = f2bf(oacc[cb][i] * invs[i]);
;     }
	v_div_scale_f32 v18, s[14:15], s9, s9, 1.0
	v_rcp_f32_e32 v19, v18
	v_lshlrev_b32_e32 v0, 1, v0
	v_fma_f32 v20, -v18, v19, 1.0
	v_fmac_f32_e32 v19, v20, v19
	v_div_scale_f32 v20, vcc, 1.0, s9, 1.0
	v_mul_f32_e32 v21, v20, v19
	v_fma_f32 v22, -v18, v21, v20
	v_fmac_f32_e32 v21, v22, v19
	v_fma_f32 v18, -v18, v21, v20
	v_div_fmas_f32 v18, v18, v19, v21
	v_div_fixup_f32 v20, v18, s9, 1.0
	v_div_scale_f32 v18, s[14:15], s8, s8, 1.0
	v_rcp_f32_e32 v19, v18
	s_nop 0
	v_fma_f32 v21, -v18, v19, 1.0
	v_fmac_f32_e32 v19, v21, v19
	v_div_scale_f32 v21, vcc, 1.0, s8, 1.0
	v_mul_f32_e32 v22, v21, v19
	v_fma_f32 v23, -v18, v22, v21
	v_fmac_f32_e32 v22, v23, v19
	v_fma_f32 v18, -v18, v22, v21
	v_div_fmas_f32 v18, v18, v19, v22
	v_div_fixup_f32 v21, v18, s8, 1.0
	v_div_scale_f32 v18, s[8:9], s1, s1, 1.0
	v_rcp_f32_e32 v19, v18
	s_nop 0
	v_fma_f32 v22, -v18, v19, 1.0
	v_fmac_f32_e32 v19, v22, v19
	v_div_scale_f32 v22, vcc, 1.0, s1, 1.0
	v_mul_f32_e32 v23, v22, v19
	v_fma_f32 v24, -v18, v23, v22
	v_fmac_f32_e32 v23, v24, v19
	v_fma_f32 v18, -v18, v23, v22
	v_div_fmas_f32 v18, v18, v19, v23
	v_div_fixup_f32 v22, v18, s1, 1.0
	v_div_scale_f32 v18, s[8:9], s0, s0, 1.0
	v_rcp_f32_e32 v19, v18
	s_nop 0
	v_fma_f32 v23, -v18, v19, 1.0
	v_fmac_f32_e32 v19, v23, v19
	v_div_scale_f32 v23, vcc, 1.0, s0, 1.0
	v_mul_f32_e32 v24, v23, v19
	v_fma_f32 v25, -v18, v24, v23
	v_fmac_f32_e32 v24, v25, v19
	v_fma_f32 v18, -v18, v24, v23
	v_div_fmas_f32 v18, v18, v19, v24
	v_div_fixup_f32 v23, v18, s0, 1.0
	v_lshlrev_b64 v[18:19], 11, v[200:201]
	s_lshl_b32 s0, s12, 8
	v_lshl_add_u64 v[18:19], s[82:83], 0, v[18:19]
	s_ashr_i32 s1, s0, 31
	v_lshl_add_u64 v[18:19], s[0:1], 1, v[18:19]
	v_lshl_add_u64 v[18:19], v[18:19], 0, v[0:1]
	v_mul_f32_e32 v0, v23, v6
	v_cvt_pk_bf16_f32 v0, v0, s0
	global_store_short v[18:19], v0, off offset:32
	v_mul_f32_e32 v0, v23, v10
	v_cvt_pk_bf16_f32 v0, v0, s0
	global_store_short v[18:19], v0, off offset:64
	v_mul_f32_e32 v0, v23, v14
	v_cvt_pk_bf16_f32 v0, v0, s0
	global_store_short v[18:19], v0, off offset:96
	v_mul_f32_e32 v0, v22, v3
	v_cvt_pk_bf16_f32 v0, v0, s0
	global_store_short v[18:19], v0, off offset:128
	v_mul_f32_e32 v0, v22, v7
	v_cvt_pk_bf16_f32 v0, v0, s0
	global_store_short v[18:19], v0, off offset:160
	v_mul_f32_e32 v0, v22, v11
	v_cvt_pk_bf16_f32 v0, v0, s0
	global_store_short v[18:19], v0, off offset:192
	v_mul_f32_e32 v0, v22, v15
	v_cvt_pk_bf16_f32 v0, v0, s0
	global_store_short v[18:19], v0, off offset:224
	v_mul_f32_e32 v0, v21, v4
	v_cvt_pk_bf16_f32 v0, v0, s0
	global_store_short v[18:19], v0, off offset:256
	v_mul_f32_e32 v0, v21, v8
	v_cvt_pk_bf16_f32 v0, v0, s0
	global_store_short v[18:19], v0, off offset:288
	v_mul_f32_e32 v0, v21, v12
	v_cvt_pk_bf16_f32 v0, v0, s0
	global_store_short v[18:19], v0, off offset:320
	v_mul_f32_e32 v0, v21, v16
	v_cvt_pk_bf16_f32 v0, v0, s0
	global_store_short v[18:19], v0, off offset:352
	v_mul_f32_e32 v0, v20, v5
	v_cvt_pk_bf16_f32 v0, v0, s0
	global_store_short v[18:19], v0, off offset:384
	v_mul_f32_e32 v0, v20, v9
	v_cvt_pk_bf16_f32 v0, v0, s0
	global_store_short v[18:19], v0, off offset:416
	v_mul_f32_e32 v0, v20, v13
	v_cvt_pk_bf16_f32 v0, v0, s0
	v_mul_f32_e32 v2, v23, v2
	global_store_short v[18:19], v0, off offset:448
	v_mul_f32_e32 v0, v20, v17
	v_cvt_pk_bf16_f32 v2, v2, s0
	v_cvt_pk_bf16_f32 v0, v0, s0
	global_store_short v[18:19], v2, off
	global_store_short v[18:19], v0, off offset:480
	s_branch .LBB0_352

; #define PG8_LAS __attribute__((address_space(3)))
; __global__ void __launch_bounds__(512, 2) mega(Params pp) {
;     ...
;     switch (op) {
;       case OP_CONVERT: phase_convert(wv_, vb_, nvb_, ws_, p, smem); break;
;       case OP_NORM_MIX: phase_norm(wv_, vb_, nvb_, xcur, p.norm_mix + l * DM, H); break;
;       case OP_GEMM_IN:
;         if (kind == 0) { pg8::EpiB16HN E; E.O = Pm; E.ldc = 4608; E.ncols_norm = 3072; E.nq_cols = 1536; E.gq = p.a_q_gain + j * 64; E.gk = p.a_k_gain + j * 64; E.T = (PG8_LAS float*)(smem0 + 131072);
;           run_gemm(wv8_, H, WT + (size_t)j * 4718592u, 4608, 1024, -1, E); }
;         else if (kind == 1) { pg8::EpiB16HN E; E.O = Pm; E.ldc = 2304; E.ncols_norm = 1280; E.nq_cols = 1024; E.gq = p.b_q_gain; E.gk = p.b_k_gain; E.T = (PG8_LAS float*)(smem0 + 131072);
;           run_gemm(wv8_, H, WT + wOff(4), 2304, 1024, -1, E); }
;         else { pg8::EpiCIn E; E.Q = (u16*)(ws_ + WS_CQKV); E.G = (u16*)(ws_ + WS_CG); E.S = (float*)(ws_ + WS_SIDE); E.half = half;
;           run_gemm(wv8_, H, WT + wOff(6), 4352, 1024, half, E); }
;         break;
;       case OP_HEADNORM:
;         if (kind == 0) phase_headnorm(wv_, vb_, nvb_, Pm, 4608, 48, 24, p.a_q_gain + j * 64, p.a_k_gain + j * 64);
;         else phase_headnorm(wv_, vb_, nvb_, Pm, 2304, 20, 16, p.b_q_gain, p.b_k_gain);
;         break;
;       case OP_ATTN_A: phase_attn_a(wv_, vb_, nvb_, ws_, p, smem); break;
;       case OP_COMBINE_A: phase_combine_a(wv_, vb_, nvb_, ws_, p); break;
;       case OP_GEMM_OUT:
;       case OP_GEMM_W2: {
;         pg8::EpiResid E; E.C = p.out; E.X = xcur;
;         const u16* Ag = H; int Kg = 1024; unsigned wo = wOff(7);
;         if (op == OP_GEMM_W2) { Ag = Pm; Kg = 4096; wo = wOff(12) + (unsigned)l * 4194304u; }
;         else if (kind == 0) { Kg = 512; wo = wOff(2) + (unsigned)j * 524288u; }
;         else if (kind == 1) { wo = wOff(5); }
;         run_gemm(wv8_, Ag, WT + wo, 1024, Kg, -1, E);
;         break; }
;       case OP_MIX_B: if (half == 0) phase_mix_b(wv_, vb_, nvb_, ws_, p, smem); else phase_mix_b2(wv_, vb_, nvb_, ws_, p, smem); break;
;       case OP_PREP_C: phase_prep_c(wv_, vb_, nvb_, ws_, p, smem, half); break;
;       case OP_SCAN_C: phase_scan_c(wv_, vb_, nvb_, ws_, p, smem, half); break;
;       case OP_SCAN_GEMM:
;         if ((int)blockIdx.x < 64) phase_scan_c(wv_, vb_, nvb_, ws_, p, smem, 0);
.LBB0_447:
	s_nop 0
	s_nop 0
	s_nop 0
	s_nop 0
	s_nop 0
	s_nop 0
	s_nop 0
	s_nop 0
	s_nop 0
	s_nop 0
	s_nop 0
	s_nop 0
	s_nop 0
	s_nop 0
	s_nop 0
	s_nop 0
	s_nop 0
	s_nop 0
	s_nop 0
	s_nop 0
	s_nop 0
	s_mov_b64 s[2:3], 0
